# passA prologue gate scans: DPP add scan, v_readlane for the last-lane broadcast and DPP max scan instead of thirteen dependent ds_bpermute round trips per chunk
# baseline (speedup 1.0000x reference)
; __device__ void passA(const Params& p, LAS unsigned char* lds, int wg) {
;     ...
;         const bool isctx = st < 2; const int ci = isctx ? (dir ? 1 - st : st) : (dir ? 15 - (st - 2) : st - 2);
;         const int T = isctx ? 256 : 2048; const float* G = isctx ? GC + (size_t)b * 16 * 256 : GL + (size_t)b * 16 * 2048;
;         const float* pli = G + (size_t)(dir * 8 + h) * T + ci * 128; const float* plf = G + (size_t)(dir * 8 + 4 + h) * T + ci * 128;
;         const int s0 = dir ? 127 - 2 * lane : 2 * lane, s1 = dir ? 126 - 2 * lane : 2 * lane + 1;
;         const float lf0 = plf[s0], lf1 = plf[s1], li0 = pli[s0], li1 = pli[s1];
;         const float p1 = lf0 + lf1; float inc = p1;
; #pragma unroll
;         for (int off = 1; off < 64; off <<= 1) { const float n = __shfl_up(inc, off); inc += (lane >= off) ? n : 0.f; }
;         const float bend = __shfl(inc, 63);
;         const float b0 = inc - p1 + lf0, b1 = inc;
;         const float w0 = bend - b0 + li0, w1 = bend - b1 + li1;
;         float mx = fmaxf(w0, w1);
; #pragma unroll
;         for (int off = 32; off > 0; off >>= 1) mx = fmaxf(mx, __shfl_xor(mx, off));
;         eA[st * 128 + s0] = w0; eA[st * 128 + s1] = w1;
;         if (lane == 0) { bendA[st] = bend; maxwA[st] = mx; }
.LBB0_378:
	s_or_saveexec_b64 s[76:77], s[76:77]
	v_mov_b64_e32 v[8:9], 0x800
	v_mov_b64_e32 v[10:11], s[50:51]
	s_xor_b64 exec, exec, s[76:77]
	v_cndmask_b32_e64 v3, v24, v28, s[0:1]
	v_mov_b64_e32 v[8:9], 0x100
	v_mov_b64_e32 v[10:11], s[52:53]
	s_or_b64 exec, exec, s[76:77]
	v_mul_u32_u24_e32 v0, s38, v8
	v_lshlrev_b32_e32 v0, 2, v0
	v_lshl_add_u64 v[30:31], v[10:11], 0, v[0:1]
	v_lshlrev_b32_e32 v32, 7, v3
	v_mul_u32_u24_e32 v0, s39, v8
	v_ashrrev_i32_e32 v33, 31, v32
	v_lshlrev_b32_e32 v0, 2, v0
	v_lshlrev_b64 v[32:33], 2, v[32:33]
	v_lshl_add_u64 v[8:9], v[10:11], 0, v[0:1]
	v_lshl_add_u64 v[8:9], v[8:9], 0, v[32:33]
	v_mov_b32_e32 v3, v1
	v_lshl_add_u64 v[10:11], v[8:9], 0, v[2:3]
	s_waitcnt lgkmcnt(0)
	v_mov_b32_e32 v7, v1
	v_lshl_add_u64 v[8:9], v[8:9], 0, v[6:7]
	global_load_dword v29, v[10:11], off
	global_load_dword v0, v[8:9], off
	v_lshl_add_u64 v[8:9], v[30:31], 0, v[32:33]
	v_lshl_add_u64 v[10:11], v[8:9], 0, v[2:3]
	v_lshl_add_u64 v[8:9], v[8:9], 0, v[6:7]
	global_load_dword v3, v[10:11], off
	global_load_dword v7, v[8:9], off
	v_add_u32_e32 v10, 0, v27
	s_waitcnt vmcnt(2)
	v_add_f32_e32 v8, v29, v0
	v_mov_b32_e32 v9, v8
	s_nop 1
	v_add_f32_dpp v9, v9, v9 row_shr:1 row_mask:0xf bank_mask:0xf
	s_nop 1
	v_add_f32_dpp v9, v9, v9 row_shr:2 row_mask:0xf bank_mask:0xf
	s_nop 1
	v_add_f32_dpp v9, v9, v9 row_shr:4 row_mask:0xf bank_mask:0xf
	s_nop 1
	v_add_f32_dpp v9, v9, v9 row_shr:8 row_mask:0xf bank_mask:0xf
	s_nop 1
	v_add_f32_dpp v9, v9, v9 row_bcast:15 row_mask:0xa bank_mask:0xf
	s_nop 1
	v_add_f32_dpp v9, v9, v9 row_bcast:31 row_mask:0xc bank_mask:0xf
	s_nop 0
	v_readlane_b32 s78, v9, 63
	v_sub_f32_e32 v8, v9, v8
	v_add_f32_e32 v8, v29, v8
	v_sub_f32_e32 v8, s78, v8
	v_sub_f32_e32 v9, s78, v9
	s_waitcnt vmcnt(1)
	v_add_f32_e32 v8, v3, v8
	s_waitcnt vmcnt(0)
	v_add_f32_e32 v9, v7, v9
	v_max_f32_e32 v3, v8, v9
	ds_write_b32 v10, v8
	v_add_u32_e32 v8, 0, v26
	ds_write_b32 v8, v9
	s_nop 1
	v_max_f32_dpp v3, v3, v3 row_shr:1 row_mask:0xf bank_mask:0xf
	s_nop 1
	v_max_f32_dpp v3, v3, v3 row_shr:2 row_mask:0xf bank_mask:0xf
	s_nop 1
	v_max_f32_dpp v3, v3, v3 row_shr:4 row_mask:0xf bank_mask:0xf
	s_nop 1
	v_max_f32_dpp v3, v3, v3 row_shr:8 row_mask:0xf bank_mask:0xf
	s_nop 1
	v_max_f32_dpp v3, v3, v3 row_bcast:15 row_mask:0xa bank_mask:0xf
	s_nop 1
	v_max_f32_dpp v3, v3, v3 row_bcast:31 row_mask:0xc bank_mask:0xf
	s_nop 0
	v_readlane_b32 s79, v3, 63
	s_and_saveexec_b64 s[76:77], s[16:17]
	s_cbranch_execz .LBB0_372
	v_add_u32_e32 v7, 0, v25
	v_add_u32_e32 v8, 0x17880, v7
	v_add_u32_e32 v7, 0x17800, v7
	v_mov_b32_e32 v0, s78
	v_mov_b32_e32 v3, s79
	ds_write_b32 v7, v0
	ds_write_b32 v8, v3
	s_branch .LBB0_372

; __device__ void passA(const Params& p, LAS unsigned char* lds, int wg) {
;     ...
;     { bool ic; int ci; const bf16_t* Kb; const bf16_t* Vb; passA_chunk(p, 0, b, h, dir, vs, ic, ci, Kb, Vb);
; #pragma unroll
;         for (int rep = 0; rep < 2; ++rep) { const int it = tid + rep * 512;
;             vr[rep] = *(const u32x4*)(Vb + (size_t)it * 8);
;             const int sq = (it & 15) | (((it >> 6) & 1) << 4), ko = ((it >> 4) & 3) | ((it >> 7) << 2); const bf16_t* src = Kb + (size_t)((sq >> 2) * 8 + (ko >> 2)) * 512 + ((sq & 3) * 16 + (ko & 3)) * 8;
;             kr[rep][0] = *(const u32x4*)src; kr[rep][1] = *(const u32x4*)(src + 32); kr[rep][2] = *(const u32x4*)(src + 64); kr[rep][3] = *(const u32x4*)(src + 96); } }
;     for (int st = 0; st < 18; ++st) {
;         bool isctx; int ci; const bf16_t* Kb; const bf16_t* Vb; passA_chunk(p, st, b, h, dir, vs, isctx, ci, Kb, Vb);
;         if (!isctx) {
;             bf16_t* cs = cst_ptr(p, sid, ci);
; #pragma unroll
;             for (int vt = 0; vt < 4; ++vt) { u32x4 w; w.x = cvt_pk_bf16(acc[0][vt][0], acc[0][vt][1]); w.y = cvt_pk_bf16(acc[0][vt][2], acc[0][vt][3]);
;                 w.z = cvt_pk_bf16(acc[1][vt][0], acc[1][vt][1]); w.w = cvt_pk_bf16(acc[1][vt][2], acc[1][vt][3]);
;                 __builtin_nontemporal_store(w, (u32x4*)(cs + (size_t)((vs * 4 + vt) * 8 + wid) * 512 + (fr * 4 + fq) * 8)); }
;             if (vs == 0) { if (fr == 0) { float* np = (float*)(p.ws + OFF_NST) + (size_t)(sid * 16 + ci) * 256 + wid * 32 + fq * 8; *(f32x4*)np = nacc[0]; *(f32x4*)(np + 4) = nacc[1]; }
;                 if (tid == 0) ((float*)(p.ws + OFF_MST))[sid * 16 + ci] = mprevA[st]; }
;         }
;         if (st == 17) break;
;         const LAS float* e_s = eA + st * 128; const float decay = decayA[st];
; #pragma unroll
;         for (int rep = 0; rep < 2; ++rep) { const int it = tid + rep * 512; const int v = (it >> 8) * 16 + ((it >> 2) & 15), sg = ((it >> 6) & 3) * 32 + (it & 3) * 8;
;             const u32x4 raw = vr[rep];
;             u32x4 w; w.x = cvt_pk_bf16(bf_lo(raw.x) * e_s[sg], bf_hi(raw.x) * e_s[sg + 1]); w.y = cvt_pk_bf16(bf_lo(raw.y) * e_s[sg + 2], bf_hi(raw.y) * e_s[sg + 3]);
;             w.z = cvt_pk_bf16(bf_lo(raw.z) * e_s[sg + 4], bf_hi(raw.z) * e_s[sg + 5]); w.w = cvt_pk_bf16(bf_lo(raw.w) * e_s[sg + 6], bf_hi(raw.w) * e_s[sg + 7]);
;             *(LAS u32x4*)(Ve + v * 136 + sg) = w; }
; #pragma unroll
.Lgb2_done:
	s_or_b64 exec, exec, s[12:13]
	s_waitcnt lgkmcnt(0)
	s_barrier
	global_load_dwordx4 v[10:13], v[0:1], off
	v_add_u32_e32 v6, 0x200, v4
	v_ashrrev_i32_e32 v7, 31, v6
	v_and_b32_e32 v100, 15, v4
	v_lshrrev_b32_e32 v0, 2, v4
	v_bfe_u32 v48, v4, 4, 2
	v_lshlrev_b32_e32 v1, 4, v4
	v_lshlrev_b64 v[84:85], 4, v[6:7]
	v_and_or_b32 v3, v0, 16, v100
	v_and_or_b32 v5, v1, 48, v48
	v_lshl_add_u64 v[0:1], s[6:7], 0, v[84:85]
	global_load_dwordx4 v[14:17], v[0:1], off
	v_mov_b32_e32 v83, 0
	v_lshlrev_b32_e32 v0, 1, v3
	v_lshlrev_b32_e32 v82, 4, v5
	v_lshlrev_b32_e32 v9, 3, v4
	v_ashrrev_i32_e32 v2, 7, v4
	v_and_b32_e32 v5, 56, v0
	v_lshl_add_u64 v[18:19], s[0:1], 0, v[82:83]
	v_lshrrev_b32_e32 v57, 1, v4
	s_movk_i32 s1, 0x60
	v_and_b32_e32 v9, 24, v9
	v_add_u32_e32 v0, v5, v2
	v_and_b32_e32 v50, 60, v8
	v_ashrrev_i32_e32 v8, 7, v6
	v_and_or_b32 v52, v57, s1, v9
	v_ashrrev_i32_e32 v1, 31, v0
	v_lshl_add_u32 v9, v52, 2, 0
	v_add_u32_e32 v8, v5, v8
	v_lshlrev_b64 v[86:87], 10, v[0:1]
	v_add_u32_e32 v91, 0x15400, v9
	v_ashrrev_i32_e32 v9, 31, v8
	v_lshl_add_u64 v[34:35], v[18:19], 0, v[86:87]
	v_lshlrev_b64 v[88:89], 10, v[8:9]
	global_load_dwordx4 v[0:3], v[34:35], off offset:192
	v_lshl_add_u64 v[8:9], v[18:19], 0, v[88:89]
	global_load_dwordx4 v[18:21], v[34:35], off offset:64
	global_load_dwordx4 v[22:25], v[34:35], off offset:128
	global_load_dwordx4 v[26:29], v[8:9], off
	global_load_dwordx4 v[30:33], v[8:9], off offset:64
	s_lshl_b32 s29, s29, 2
	global_load_dwordx4 v[34:37], v[34:35], off
	s_and_b32 s38, s29, 0x1f0
	s_cmp_eq_u32 s34, 0
	s_cselect_b64 s[6:7], -1, 0
	s_add_i32 s1, 0, 0x17900
	v_mov_b32_e32 v5, s1
	ds_read_b32 v53, v5
	ds_read_b64 v[46:47], v91
	global_load_dwordx4 v[38:41], v[8:9], off offset:128
	global_load_dwordx4 v[42:45], v[8:9], off offset:192
	v_lshrrev_b32_e32 v7, 4, v4
	v_bfe_u32 v49, v4, 2, 4
	s_mov_b32 s9, 0xffffff0
	v_and_b32_e32 v51, 64, v4
	s_movk_i32 s0, 0x110
	v_and_or_b32 v7, v7, s9, v49
	s_add_i32 s1, 0, 0x11000
	v_mul_lo_u32 v7, v7, s0
	v_lshlrev_b32_e32 v111, 1, v4
	v_lshlrev_b32_e32 v90, 5, v56
	v_and_b32_e32 v112, 3, v4
	v_and_b32_e32 v105, 48, v4
	v_add_u32_e32 v113, s1, v105
	v_lshrrev_b32_e32 v4, 5, v4
	s_mov_b32 s39, 0xffff0000
	s_xor_b32 s8, s8, 1
	v_readlane_b32 s16, v254, 31
	v_readlane_b32 s17, v254, 32
	v_lshl_add_u64 v[102:103], s[30:31], 0, v[82:83]
	s_mov_b32 s40, 0
	s_waitcnt vmcnt(9)
	v_and_b32_e32 v8, 0xffff0000, v10
	v_lshlrev_b32_e32 v5, 16, v10
	s_waitcnt lgkmcnt(0)
	v_mul_f32_e32 v8, v47, v8
	v_mul_f32_e32 v5, v46, v5
	v_cvt_pk_bf16_f32 v8, v5, v8
	ds_read_b64 v[46:47], v91 offset:8
	v_lshlrev_b32_e32 v9, 16, v11
	v_and_b32_e32 v10, 0xffff0000, v11
	v_lshlrev_b32_e32 v5, 1, v51
	v_lshl_add_u32 v51, v52, 1, s1
	s_waitcnt lgkmcnt(0)
	v_mul_f32_e32 v9, v46, v9
	v_mul_f32_e32 v10, v47, v10
	v_cvt_pk_bf16_f32 v9, v9, v10
	ds_read_b64 v[10:11], v91 offset:16
	v_lshlrev_b32_e32 v46, 16, v12
	v_and_b32_e32 v12, 0xffff0000, v12
	v_add_u32_e32 v106, v51, v7
	v_lshlrev_b32_e32 v7, 16, v13
	s_waitcnt lgkmcnt(0)
	v_mul_f32_e32 v10, v10, v46
	v_mul_f32_e32 v11, v11, v12
	v_cvt_pk_bf16_f32 v10, v10, v11
	ds_read_b64 v[46:47], v91 offset:24
	v_and_b32_e32 v11, 0xffff0000, v13
	v_and_b32_e32 v12, 24, v111
	s_mov_b32 s1, 0x1fffffc
	v_and_or_b32 v4, v4, s1, v48
	s_waitcnt lgkmcnt(0)
	v_mul_f32_e32 v11, v47, v11
	v_mul_f32_e32 v7, v46, v7
	v_cvt_pk_bf16_f32 v11, v7, v11
	ds_write_b128 v106, v[8:11]
	ds_read_b64 v[8:9], v91
	s_waitcnt vmcnt(8)
	v_lshlrev_b32_e32 v10, 16, v14
	v_and_b32_e32 v11, 0xffff0000, v14
	v_lshlrev_b32_e32 v7, 1, v50
	v_add3_u32 v7, 0, v5, v7
	s_waitcnt lgkmcnt(0)
	v_mul_f32_e32 v8, v8, v10
	v_mul_f32_e32 v9, v9, v11
	v_cvt_pk_bf16_f32 v8, v8, v9
	ds_read_b64 v[10:11], v91 offset:8
	v_and_b32_e32 v9, 0xffff0000, v15
	v_lshlrev_b32_e32 v5, 16, v15
	v_or3_b32 v14, v112, v12, v90
	v_and_b32_e32 v12, 0xffff0000, v16
	s_waitcnt lgkmcnt(0)
	v_mul_f32_e32 v9, v11, v9
	v_mul_f32_e32 v5, v10, v5
	v_cvt_pk_bf16_f32 v9, v5, v9
	ds_read_b64 v[10:11], v91 offset:16
	v_lshlrev_b32_e32 v5, 16, v16
	v_add_u32_e32 v46, 0, v105
	s_waitcnt lgkmcnt(0)
	v_mul_f32_e32 v5, v10, v5
	v_mul_f32_e32 v10, v11, v12
	v_cvt_pk_bf16_f32 v10, v5, v10
	ds_read_b64 v[12:13], v91 offset:24
	v_lshrrev_b32_e32 v5, 4, v6
	v_and_or_b32 v5, v5, s9, v49
	v_lshlrev_b32_e32 v11, 16, v17
	v_mul_lo_u32 v5, v5, s0
	s_movk_i32 s9, 0x880
	s_waitcnt lgkmcnt(0)
	v_mul_f32_e32 v11, v12, v11
	v_and_b32_e32 v12, 0xffff0000, v17
	v_add_u32_e32 v107, v51, v5
	v_mul_lo_u32 v4, v4, s9
	v_mul_f32_e32 v12, v13, v12
	v_cvt_pk_bf16_f32 v11, v11, v12
	ds_write_b128 v107, v[8:11]
	v_add_u32_e32 v108, v7, v4
	s_waitcnt vmcnt(2)
	v_and_b32_e32 v4, 0xffff, v34
	v_and_b32_e32 v5, 0xffff, v22
	v_lshrrev_b32_e32 v8, 16, v34
	v_lshrrev_b32_e32 v9, 16, v22
	v_lshl_or_b32 v4, v18, 16, v4
	v_lshl_or_b32 v5, v0, 16, v5
	v_and_or_b32 v8, v18, s39, v8
	v_and_or_b32 v9, v0, s39, v9
	v_and_b32_e32 v0, 0xffff, v35
	ds_write2_b64 v108, v[4:5], v[8:9] offset1:34
	v_lshl_or_b32 v4, v19, 16, v0
	v_and_b32_e32 v0, 0xffff, v23
	v_lshl_or_b32 v5, v1, 16, v0
	v_lshrrev_b32_e32 v0, 16, v35
	v_lshrrev_b32_e32 v8, 16, v23
	v_and_or_b32 v0, v19, s39, v0
	v_and_or_b32 v1, v1, s39, v8
	ds_write2_b64 v108, v[4:5], v[0:1] offset0:68 offset1:102
	v_and_b32_e32 v0, 0xffff, v36
	v_and_b32_e32 v1, 0xffff, v24
	v_lshrrev_b32_e32 v4, 16, v36
	v_lshrrev_b32_e32 v5, 16, v24
	v_lshl_or_b32 v0, v20, 16, v0
	v_lshl_or_b32 v1, v2, 16, v1
	v_and_or_b32 v4, v20, s39, v4
	v_and_or_b32 v5, v2, s39, v5
	ds_write2_b64 v108, v[0:1], v[4:5] offset0:136 offset1:170
	v_and_b32_e32 v0, 0xffff, v37
	v_and_b32_e32 v1, 0xffff, v25
	v_lshrrev_b32_e32 v2, 16, v37
	v_lshrrev_b32_e32 v4, 16, v25
	v_lshl_or_b32 v0, v21, 16, v0
	v_lshl_or_b32 v1, v3, 16, v1
	v_and_or_b32 v2, v21, s39, v2
	v_and_or_b32 v3, v3, s39, v4
	ds_write2_b64 v108, v[0:1], v[2:3] offset0:204 offset1:238
	v_lshrrev_b32_e32 v0, 5, v6
	v_and_or_b32 v0, v0, s1, v48
	v_mul_lo_u32 v0, v0, s9
	v_add_u32_e32 v109, v7, v0
	v_and_b32_e32 v0, 0xffff, v26
	s_waitcnt vmcnt(1)
; __device__ void passA(const Params& p, LAS unsigned char* lds, int wg) {
;     ...
;         for (int rep = 0; rep < 2; ++rep) { const int it = tid + rep * 512; const int sq = (it & 15) | (((it >> 6) & 1) << 4), ko = ((it >> 4) & 3) | ((it >> 7) << 2);
;             const u32x4 r0 = kr[rep][0], r1 = kr[rep][1], r2 = kr[rep][2], r3 = kr[rep][3];
;             LAS bf16_t* dst = Kt + (ko * 8) * 136 + sq * 4;
;     ...
;             TRW(0, r0.x, r1.x, r2.x, r3.x, 0) TRW(1, r0.x, r1.x, r2.x, r3.x, 1) TRW(2, r0.y, r1.y, r2.y, r3.y, 0) TRW(3, r0.y, r1.y, r2.y, r3.y, 1)
;             TRW(4, r0.z, r1.z, r2.z, r3.z, 0) TRW(5, r0.z, r1.z, r2.z, r3.z, 1) TRW(6, r0.w, r1.w, r2.w, r3.w, 0) TRW(7, r0.w, r1.w, r2.w, r3.w, 1)
;     ...
;         }
;         __syncthreads();
;         if (st + 1 < 17) {
;             bool ic2; int ci2; const bf16_t* Kb2; const bf16_t* Vb2; passA_chunk(p, st + 1, b, h, dir, vs, ic2, ci2, Kb2, Vb2);
; #pragma unroll
;             for (int rep = 0; rep < 2; ++rep) { const int it = tid + rep * 512;
;                 vr[rep] = *(const u32x4*)(Vb2 + (size_t)it * 8);
;                 const int sq = (it & 15) | (((it >> 6) & 1) << 4), ko = ((it >> 4) & 3) | ((it >> 7) << 2); const bf16_t* src = Kb2 + (size_t)((sq >> 2) * 8 + (ko >> 2)) * 512 + ((sq & 3) * 16 + (ko & 3)) * 8;
;                 kr[rep][0] = *(const u32x4*)src; kr[rep][1] = *(const u32x4*)(src + 32); kr[rep][2] = *(const u32x4*)(src + 64); kr[rep][3] = *(const u32x4*)(src + 96); } }
; #pragma unroll
;         for (int a = 0; a < 2; ++a) { nacc[a] *= decay;
; #pragma unroll
;             for (int v = 0; v < 4; ++v) acc[a][v] *= decay; }
; #pragma unroll
;         for (int ks = 0; ks < 4; ++ks) { bf16x8 kf[2], vf[4];
; #pragma unroll
;             for (int kt = 0; kt < 2; ++kt) kf[kt] = *(const LAS bf16x8*)(Kt + (wid * 32 + 8 * (fr >> 2) + 4 * kt + (fr & 3)) * 136 + ks * 32 + fq * 8);
; #pragma unroll
;             for (int vt = 0; vt < 4; ++vt) vf[vt] = *(const LAS bf16x8*)(Ve + (vt * 16 + fr) * 136 + ks * 32 + fq * 8);
;             bf16x8 ef = *(const LAS bf16x8*)(eB + st * 128 + ks * 32 + fq * 8);
;             if (fr != 0) ef = (bf16x8){0, 0, 0, 0, 0, 0, 0, 0};
; #pragma unroll
;             for (int kt = 0; kt < 2; ++kt) {
; #pragma unroll
;                 for (int vt = 0; vt < 4; ++vt) acc[kt][vt] = __builtin_amdgcn_mfma_f32_16x16x32_bf16(kf[kt], vf[vt], acc[kt][vt], 0, 0, 0);
	v_and_b32_e32 v1, 0xffff, v38
	v_lshrrev_b32_e32 v2, 16, v26
	v_lshrrev_b32_e32 v3, 16, v38
	v_lshl_or_b32 v0, v30, 16, v0
	s_waitcnt vmcnt(0)
	v_lshl_or_b32 v1, v42, 16, v1
	v_and_or_b32 v2, v30, s39, v2
	v_and_or_b32 v3, v42, s39, v3
	ds_write2_b64 v109, v[0:1], v[2:3] offset1:34
	v_and_b32_e32 v0, 0xffff, v27
	v_and_b32_e32 v1, 0xffff, v39
	v_lshrrev_b32_e32 v2, 16, v27
	v_lshrrev_b32_e32 v3, 16, v39
	v_lshl_or_b32 v0, v31, 16, v0
	v_lshl_or_b32 v1, v43, 16, v1
	v_and_or_b32 v2, v31, s39, v2
	v_and_or_b32 v3, v43, s39, v3
	ds_write2_b64 v109, v[0:1], v[2:3] offset0:68 offset1:102
	v_and_b32_e32 v0, 0xffff, v28
	v_and_b32_e32 v1, 0xffff, v40
	v_lshrrev_b32_e32 v2, 16, v28
	v_lshrrev_b32_e32 v3, 16, v40
	v_lshl_or_b32 v0, v32, 16, v0
	v_lshl_or_b32 v1, v44, 16, v1
	v_and_or_b32 v2, v32, s39, v2
	v_and_or_b32 v3, v44, s39, v3
	ds_write2_b64 v109, v[0:1], v[2:3] offset0:136 offset1:170
	v_and_b32_e32 v0, 0xffff, v29
	v_and_b32_e32 v1, 0xffff, v41
	v_lshrrev_b32_e32 v2, 16, v29
	v_lshrrev_b32_e32 v3, 16, v41
	v_lshl_or_b32 v0, v33, 16, v0
	v_lshl_or_b32 v1, v45, 16, v1
	v_and_or_b32 v2, v33, s39, v2
	v_and_or_b32 v3, v45, s39, v3
	ds_write2_b64 v109, v[0:1], v[2:3] offset0:204 offset1:238
	v_mul_lo_u32 v1, v14, s0
	v_add_u32_e32 v110, v46, v1
	s_waitcnt lgkmcnt(0)
	s_barrier
	ds_read_b128 v[4:7], v110
	v_mad_u32_u24 v29, v100, s0, v113
	ds_read_b128 v[8:11], v29
	v_add_u32_e32 v30, 0x17a80, v46
	v_mul_f32_e32 v0, 0, v53
	ds_read_b128 v[12:15], v29 offset:4352
	ds_read_b128 v[16:19], v110 offset:64
	ds_read_b128 v[20:23], v29 offset:64
	ds_read_b128 v[32:35], v29 offset:8704
	ds_read_b128 v[36:39], v29 offset:4416
	ds_read_b128 v[44:47], v29 offset:13056
	ds_read_b128 v[48:51], v30
	ds_read_b128 v[52:55], v29 offset:8768
	ds_read_b128 v[62:65], v30 offset:64
	ds_read_b128 v[66:69], v29 offset:13120
	ds_read_b128 v[74:77], v110 offset:1088
	ds_read_b128 v[92:95], v110 offset:1152
	v_mov_b32_e32 v1, v0
	v_mov_b32_e32 v2, v0
	v_mov_b32_e32 v3, v0
	s_lshl_b32 s9, s8, 2
	s_or_b32 s12, s9, s25
	s_waitcnt lgkmcnt(12)
	v_mfma_f32_16x16x32_bf16 v[24:27], v[4:7], v[8:11], v[0:3]
	v_cmp_eq_u32_e64 s[0:1], 0, v100
	s_ashr_i32 s13, s12, 31
	s_lshl_b64 s[12:13], s[12:13], 16
	s_waitcnt lgkmcnt(1)
	v_mfma_f32_16x16x32_bf16 v[8:11], v[74:77], v[8:11], v[0:3]
	v_cndmask_b32_e64 v51, 0, v51, s[0:1]
	v_cndmask_b32_e64 v50, 0, v50, s[0:1]
	v_cndmask_b32_e64 v49, 0, v49, s[0:1]
	v_mfma_f32_16x16x32_bf16 v[40:43], v[4:7], v[12:15], v[0:3]
	v_cndmask_b32_e64 v48, 0, v48, s[0:1]
	s_add_u32 s12, s11, s12
	s_addc_u32 s13, s14, s13
	v_mfma_f32_16x16x32_bf16 v[12:15], v[74:77], v[12:15], v[0:3]
	s_ashr_i32 s9, s8, 31
	s_lshl_b64 s[8:9], s[8:9], 18
	s_add_u32 s3, s3, s8
	v_mfma_f32_16x16x32_bf16 v[24:27], v[16:19], v[20:23], v[24:27]
	s_addc_u32 s9, s27, s9
	s_add_u32 s8, s3, s10
	s_addc_u32 s9, s9, 0
	s_waitcnt lgkmcnt(0)
	v_mfma_f32_16x16x32_bf16 v[8:11], v[92:95], v[20:23], v[8:11]
	ds_read_b128 v[20:23], v110 offset:128
	v_lshl_add_u64 v[78:79], s[8:9], 0, v[84:85]
	s_add_i32 s3, 0, 0x17904
	v_mfma_f32_16x16x32_bf16 v[58:61], v[4:7], v[32:35], v[0:3]
	s_cmp_eq_u32 s28, 0
	s_mov_b32 s27, 2
	s_mov_b32 s28, 14
	v_mfma_f32_16x16x32_bf16 v[70:73], v[4:7], v[44:47], v[0:3]
	v_mfma_f32_16x16x32_bf16 v[4:7], v[4:7], v[48:51], v[0:3]
	v_mfma_f32_16x16x32_bf16 v[32:35], v[74:77], v[32:35], v[0:3]
	v_mfma_f32_16x16x32_bf16 v[44:47], v[74:77], v[44:47], v[0:3]
	v_mfma_f32_16x16x32_bf16 v[0:3], v[74:77], v[48:51], v[0:3]
	v_mfma_f32_16x16x32_bf16 v[40:43], v[16:19], v[36:39], v[40:43]
	v_mfma_f32_16x16x32_bf16 v[12:15], v[92:95], v[36:39], v[12:15]
	ds_read_b128 v[36:39], v29 offset:128
	v_mfma_f32_16x16x32_bf16 v[48:51], v[16:19], v[52:55], v[58:61]
	s_nop 2
	v_cndmask_b32_e64 v61, 0, v65, s[0:1]
	v_cndmask_b32_e64 v60, 0, v64, s[0:1]
	v_cndmask_b32_e64 v59, 0, v63, s[0:1]
	v_cndmask_b32_e64 v58, 0, v62, s[0:1]
	v_mfma_f32_16x16x32_bf16 v[70:73], v[16:19], v[66:69], v[70:73]
	s_nop 0
	v_mfma_f32_16x16x32_bf16 v[4:7], v[16:19], v[58:61], v[4:7]
	v_mfma_f32_16x16x32_bf16 v[16:19], v[92:95], v[52:55], v[32:35]
	v_mfma_f32_16x16x32_bf16 v[32:35], v[92:95], v[66:69], v[44:47]
	v_mfma_f32_16x16x32_bf16 v[0:3], v[92:95], v[58:61], v[0:3]
	s_nop 1
	ds_read_b128 v[44:47], v29 offset:4480
	ds_read_b128 v[52:55], v110 offset:192
	ds_read_b128 v[58:61], v29 offset:192
	ds_read_b128 v[62:65], v110 offset:1216
	ds_read_b128 v[66:69], v29 offset:8832
	ds_read_b128 v[74:77], v29 offset:4544
	ds_read_b128 v[92:95], v30 offset:128
	ds_read_b128 v[96:99], v29 offset:13184
	ds_read_b128 v[114:117], v29 offset:8896
	s_waitcnt lgkmcnt(9)
	v_mfma_f32_16x16x32_bf16 v[24:27], v[20:23], v[36:39], v[24:27]
	ds_read_b128 v[118:121], v30 offset:192
	ds_read_b128 v[122:125], v29 offset:13248
	s_waitcnt lgkmcnt(4)
	v_cndmask_b32_e64 v95, 0, v95, s[0:1]
	v_mfma_f32_16x16x32_bf16 v[8:11], v[62:65], v[36:39], v[8:11]
	v_lshl_add_u64 v[36:37], s[8:9], 0, v[80:81]
	global_load_dwordx4 v[36:39], v[36:37], off
	v_cndmask_b32_e64 v94, 0, v94, s[0:1]
	v_mfma_f32_16x16x32_bf16 v[40:43], v[20:23], v[44:47], v[40:43]
	v_cndmask_b32_e64 v93, 0, v93, s[0:1]
	v_cndmask_b32_e64 v92, 0, v92, s[0:1]
	s_cselect_b64 s[8:9], -1, 0
	v_mfma_f32_16x16x32_bf16 v[48:51], v[20:23], v[66:69], v[48:51]
	v_mfma_f32_16x16x32_bf16 v[12:15], v[62:65], v[44:47], v[12:15]
	v_mfma_f32_16x16x32_bf16 v[44:47], v[62:65], v[66:69], v[16:19]
	global_load_dwordx4 v[66:69], v[78:79], off
	s_waitcnt vmcnt(0)
	v_lshlrev_b32_e32 v31, 16, v68
	v_lshl_add_u64 v[16:17], s[12:13], 0, v[82:83]
	v_lshl_add_u64 v[18:19], v[16:17], 0, v[86:87]
	s_waitcnt lgkmcnt(3)
	v_mfma_f32_16x16x32_bf16 v[70:73], v[20:23], v[96:99], v[70:73]
	global_load_dwordx4 v[126:129], v[18:19], off
	s_and_b64 s[12:13], s[8:9], exec
	s_cselect_b32 s11, 0, 15
	v_mfma_f32_16x16x32_bf16 v[32:35], v[62:65], v[96:99], v[32:35]
	global_load_dwordx4 v[96:99], v[18:19], off offset:192
	v_mfma_f32_16x16x32_bf16 v[4:7], v[20:23], v[92:95], v[4:7]
	ds_read_b128 v[20:23], v110 offset:1280
	v_mfma_f32_16x16x32_bf16 v[62:65], v[62:65], v[92:95], v[0:3]
	global_load_dwordx4 v[92:95], v[18:19], off offset:64
	global_load_dwordx4 v[130:133], v[18:19], off offset:128
	s_nop 0
	v_lshl_add_u64 v[0:1], v[16:17], 0, v[88:89]
	global_load_dwordx4 v[138:141], v[0:1], off
	global_load_dwordx4 v[142:145], v[0:1], off offset:64
	global_load_dwordx4 v[146:149], v[0:1], off offset:128
	global_load_dwordx4 v[150:153], v[0:1], off offset:192
	s_waitcnt lgkmcnt(0)
	s_barrier
; __device__ void passA(const Params& p, LAS unsigned char* lds, int wg) {
;     ...
;         const LAS float* e_s = eA + st * 128; const float decay = decayA[st];
; #pragma unroll
;         for (int rep = 0; rep < 2; ++rep) { const int it = tid + rep * 512; const int v = (it >> 8) * 16 + ((it >> 2) & 15), sg = ((it >> 6) & 3) * 32 + (it & 3) * 8;
;             const u32x4 raw = vr[rep];
;             u32x4 w; w.x = cvt_pk_bf16(bf_lo(raw.x) * e_s[sg], bf_hi(raw.x) * e_s[sg + 1]); w.y = cvt_pk_bf16(bf_lo(raw.y) * e_s[sg + 2], bf_hi(raw.y) * e_s[sg + 3]);
;             w.z = cvt_pk_bf16(bf_lo(raw.z) * e_s[sg + 4], bf_hi(raw.z) * e_s[sg + 5]); w.w = cvt_pk_bf16(bf_lo(raw.w) * e_s[sg + 6], bf_hi(raw.w) * e_s[sg + 7]);
;             *(LAS u32x4*)(Ve + v * 136 + sg) = w; }
; #pragma unroll
;         for (int rep = 0; rep < 2; ++rep) { const int it = tid + rep * 512; const int sq = (it & 15) | (((it >> 6) & 1) << 4), ko = ((it >> 4) & 3) | ((it >> 7) << 2);
;             const u32x4 r0 = kr[rep][0], r1 = kr[rep][1], r2 = kr[rep][2], r3 = kr[rep][3];
;             LAS bf16_t* dst = Kt + (ko * 8) * 136 + sq * 4;
;     ...
;             TRW(0, r0.x, r1.x, r2.x, r3.x, 0) TRW(1, r0.x, r1.x, r2.x, r3.x, 1) TRW(2, r0.y, r1.y, r2.y, r3.y, 0) TRW(3, r0.y, r1.y, r2.y, r3.y, 1)
;             TRW(4, r0.z, r1.z, r2.z, r3.z, 0) TRW(5, r0.z, r1.z, r2.z, r3.z, 1) TRW(6, r0.w, r1.w, r2.w, r3.w, 0) TRW(7, r0.w, r1.w, r2.w, r3.w, 1)
;     ...
;         }
;         __syncthreads();
;         if (st + 1 < 17) {
;             bool ic2; int ci2; const bf16_t* Kb2; const bf16_t* Vb2; passA_chunk(p, st + 1, b, h, dir, vs, ic2, ci2, Kb2, Vb2);
; #pragma unroll
;             for (int rep = 0; rep < 2; ++rep) { const int it = tid + rep * 512;
;                 vr[rep] = *(const u32x4*)(Vb2 + (size_t)it * 8);
;                 const int sq = (it & 15) | (((it >> 6) & 1) << 4), ko = ((it >> 4) & 3) | ((it >> 7) << 2); const bf16_t* src = Kb2 + (size_t)((sq >> 2) * 8 + (ko >> 2)) * 512 + ((sq & 3) * 16 + (ko & 3)) * 8;
;                 kr[rep][0] = *(const u32x4*)src; kr[rep][1] = *(const u32x4*)(src + 32); kr[rep][2] = *(const u32x4*)(src + 64); kr[rep][3] = *(const u32x4*)(src + 96); } }
; #pragma unroll
;         for (int a = 0; a < 2; ++a) { nacc[a] *= decay;
; #pragma unroll
;             for (int v = 0; v < 4; ++v) acc[a][v] *= decay; }
; #pragma unroll
;         for (int ks = 0; ks < 4; ++ks) { bf16x8 kf[2], vf[4];
	ds_read_b64 v[0:1], v91 offset:512
	v_mov_b32_e32 v2, s3
	ds_read_b32 v28, v2
	v_lshlrev_b32_e32 v2, 16, v36
	v_mfma_f32_16x16x32_bf16 v[16:19], v[52:55], v[114:117], v[48:51]
	s_waitcnt lgkmcnt(1)
	v_mul_f32_e32 v0, v0, v2
	v_and_b32_e32 v2, 0xffff0000, v36
	v_mul_f32_e32 v1, v1, v2
	v_cvt_pk_bf16_f32 v36, v0, v1
	ds_read_b64 v[0:1], v91 offset:520
	v_lshlrev_b32_e32 v2, 16, v37
	v_cndmask_b32_e64 v51, 0, v121, s[0:1]
	v_cndmask_b32_e64 v50, 0, v120, s[0:1]
	v_cndmask_b32_e64 v49, 0, v119, s[0:1]
	s_waitcnt lgkmcnt(0)
	v_mul_f32_e32 v0, v0, v2
	v_and_b32_e32 v2, 0xffff0000, v37
	v_mul_f32_e32 v1, v1, v2
	v_cvt_pk_bf16_f32 v37, v0, v1
	ds_read_b64 v[0:1], v91 offset:528
	v_lshlrev_b32_e32 v2, 16, v38
	v_cndmask_b32_e64 v48, 0, v118, s[0:1]
	v_mfma_f32_16x16x32_bf16 v[134:137], v[52:55], v[58:61], v[24:27]
	v_mul_f32_e64 v18, v18, v28
	v_mul_f32_e64 v19, v19, v28
	s_waitcnt lgkmcnt(0)
	v_mul_f32_e32 v0, v0, v2
	v_and_b32_e32 v2, 0xffff0000, v38
	v_mfma_f32_16x16x32_bf16 v[40:43], v[52:55], v[74:77], v[40:43]
	v_mul_f32_e32 v1, v1, v2
	v_cvt_pk_bf16_f32 v38, v0, v1
	v_pk_mul_f32 v[16:17], v[16:17], v[28:29] op_sel_hi:[1,0]
	v_mfma_f32_16x16x32_bf16 v[24:27], v[52:55], v[122:125], v[70:73]
	s_lshl_b32 s3, s46, 4
	s_nop 3
	v_pk_mul_f32 v[42:43], v[42:43], v[28:29] op_sel_hi:[1,0]
	v_pk_mul_f32 v[40:41], v[40:41], v[28:29] op_sel_hi:[1,0]
	v_mfma_f32_16x16x32_bf16 v[52:55], v[52:55], v[48:51], v[4:7]
	s_or_b32 s12, s11, s3
	v_pk_mul_f32 v[26:27], v[26:27], v[28:29] op_sel_hi:[1,0]
	v_pk_mul_f32 v[24:25], v[24:25], v[28:29] op_sel_hi:[1,0]
	ds_read_b64 v[4:5], v91 offset:536
	v_lshlrev_b32_e32 v6, 16, v39
	v_mfma_f32_16x16x32_bf16 v[0:3], v[20:23], v[58:61], v[8:11]
	s_lshl_b32 s11, s12, 2
	s_or_b32 s14, s11, s25
	s_waitcnt lgkmcnt(0)
	v_mul_f32_e32 v4, v4, v6
	v_and_b32_e32 v6, 0xffff0000, v39
	v_mul_f32_e32 v5, v5, v6
	v_cvt_pk_bf16_f32 v39, v4, v5
	ds_write_b128 v106, v[36:39]
	ds_read_b64 v[8:9], v91 offset:512
	v_lshlrev_b32_e32 v10, 16, v66
	v_mfma_f32_16x16x32_bf16 v[4:7], v[20:23], v[74:77], v[12:15]
	v_mul_f32_e64 v2, v2, v28
	v_mul_f32_e64 v3, v3, v28
	v_pk_mul_f32 v[0:1], v[0:1], v[28:29] op_sel_hi:[1,0]
	s_waitcnt lgkmcnt(0)
	v_mul_f32_e32 v8, v8, v10
	v_and_b32_e32 v10, 0xffff0000, v66
	v_mul_f32_e32 v9, v9, v10
	v_cvt_pk_bf16_f32 v36, v8, v9
	ds_read_b64 v[12:13], v91 offset:520
	v_lshlrev_b32_e32 v14, 16, v67
	v_mfma_f32_16x16x32_bf16 v[8:11], v[20:23], v[114:117], v[44:47]
	v_mul_f32_e64 v6, v6, v28
	v_mul_f32_e64 v7, v7, v28
	v_pk_mul_f32 v[4:5], v[4:5], v[28:29] op_sel_hi:[1,0]
	s_waitcnt lgkmcnt(0)
	v_mul_f32_e32 v12, v12, v14
	v_and_b32_e32 v14, 0xffff0000, v67
	v_mul_f32_e32 v13, v13, v14
	v_cvt_pk_bf16_f32 v37, v12, v13
	ds_read_b64 v[38:39], v91 offset:528
	v_mfma_f32_16x16x32_bf16 v[12:15], v[20:23], v[122:125], v[32:35]
	v_mul_f32_e64 v10, v10, v28
	v_mul_f32_e64 v11, v11, v28
	v_pk_mul_f32 v[8:9], v[8:9], v[28:29] op_sel_hi:[1,0]
	s_ashr_i32 s15, s14, 31
	v_and_b32_e32 v32, 0xffff0000, v68
	s_waitcnt lgkmcnt(0)
	v_mul_f32_e32 v32, v39, v32
	v_mul_f32_e32 v31, v38, v31
	v_cvt_pk_bf16_f32 v38, v31, v32
	ds_read_b64 v[32:33], v91 offset:536
	v_lshlrev_b32_e32 v31, 16, v69
	v_mfma_f32_16x16x32_bf16 v[20:23], v[20:23], v[48:51], v[62:65]
	v_mul_f32_e64 v14, v14, v28
	v_mul_f32_e64 v15, v15, v28
	v_pk_mul_f32 v[12:13], v[12:13], v[28:29] op_sel_hi:[1,0]
	s_waitcnt lgkmcnt(0)
	v_mul_f32_e32 v31, v32, v31
	v_and_b32_e32 v32, 0xffff0000, v69
	v_mul_f32_e32 v32, v33, v32
	v_cvt_pk_bf16_f32 v39, v31, v32
	s_waitcnt vmcnt(7)
	v_and_b32_e32 v31, 0xffff, v126
	s_waitcnt vmcnt(5)
	v_lshl_or_b32 v32, v92, 16, v31
	s_waitcnt vmcnt(4)
	v_and_b32_e32 v31, 0xffff, v130
	v_lshl_or_b32 v33, v96, 16, v31
	v_lshrrev_b32_e32 v31, 16, v126
	v_and_or_b32 v34, v92, s39, v31
	v_lshrrev_b32_e32 v31, 16, v130
	v_and_or_b32 v35, v96, s39, v31
	v_and_b32_e32 v31, 0xffff, v127
	ds_write_b128 v107, v[36:39]
	ds_write2_b64 v108, v[32:33], v[34:35] offset1:34
	v_lshl_or_b32 v32, v93, 16, v31
	v_and_b32_e32 v31, 0xffff, v131
	v_lshl_or_b32 v33, v97, 16, v31
	v_lshrrev_b32_e32 v31, 16, v127
	v_and_or_b32 v34, v93, s39, v31
	v_lshrrev_b32_e32 v31, 16, v131
	v_and_or_b32 v35, v97, s39, v31
	v_and_b32_e32 v31, 0xffff, v128
	ds_write2_b64 v108, v[32:33], v[34:35] offset0:68 offset1:102
	v_lshl_or_b32 v32, v94, 16, v31
	v_and_b32_e32 v31, 0xffff, v132
	v_lshl_or_b32 v33, v98, 16, v31
	v_lshrrev_b32_e32 v31, 16, v128
	v_and_or_b32 v34, v94, s39, v31
	v_lshrrev_b32_e32 v31, 16, v132
	v_and_or_b32 v35, v98, s39, v31
	v_and_b32_e32 v31, 0xffff, v129
	ds_write2_b64 v108, v[32:33], v[34:35] offset0:136 offset1:170
	v_lshl_or_b32 v32, v95, 16, v31
	v_and_b32_e32 v31, 0xffff, v133
	v_lshl_or_b32 v33, v99, 16, v31
	v_lshrrev_b32_e32 v31, 16, v129
	v_and_or_b32 v34, v95, s39, v31
	v_lshrrev_b32_e32 v31, 16, v133
	v_and_or_b32 v35, v99, s39, v31
	s_waitcnt vmcnt(3)
	v_and_b32_e32 v31, 0xffff, v138
	ds_write2_b64 v108, v[32:33], v[34:35] offset0:204 offset1:238
	s_waitcnt vmcnt(2)
	v_lshl_or_b32 v32, v142, 16, v31
	s_waitcnt vmcnt(1)
	v_and_b32_e32 v31, 0xffff, v146
	s_waitcnt vmcnt(0)
	v_lshl_or_b32 v33, v150, 16, v31
	v_lshrrev_b32_e32 v31, 16, v138
	v_and_or_b32 v34, v142, s39, v31
	v_lshrrev_b32_e32 v31, 16, v146
	v_and_or_b32 v35, v150, s39, v31
	v_and_b32_e32 v31, 0xffff, v139
	ds_write2_b64 v109, v[32:33], v[34:35] offset1:34
	v_lshl_or_b32 v32, v143, 16, v31
	v_and_b32_e32 v31, 0xffff, v147
	v_lshl_or_b32 v33, v151, 16, v31
	v_lshrrev_b32_e32 v31, 16, v139
	v_and_or_b32 v34, v143, s39, v31
	v_lshrrev_b32_e32 v31, 16, v147
	v_and_or_b32 v35, v151, s39, v31
	v_and_b32_e32 v31, 0xffff, v140
	ds_write2_b64 v109, v[32:33], v[34:35] offset0:68 offset1:102
	v_lshl_or_b32 v32, v144, 16, v31
	v_and_b32_e32 v31, 0xffff, v148
	v_lshl_or_b32 v33, v152, 16, v31
	v_lshrrev_b32_e32 v31, 16, v140
	v_and_or_b32 v34, v144, s39, v31
	v_lshrrev_b32_e32 v31, 16, v148
	v_and_or_b32 v35, v152, s39, v31
	v_and_b32_e32 v31, 0xffff, v141
	ds_write2_b64 v109, v[32:33], v[34:35] offset0:136 offset1:170
	v_lshl_or_b32 v32, v145, 16, v31
	v_and_b32_e32 v31, 0xffff, v149
	v_lshl_or_b32 v33, v153, 16, v31
	v_lshrrev_b32_e32 v31, 16, v141
	v_and_or_b32 v34, v145, s39, v31
	v_lshrrev_b32_e32 v31, 16, v149
	v_and_or_b32 v35, v153, s39, v31
	ds_write2_b64 v109, v[32:33], v[34:35] offset0:204 offset1:238
	s_waitcnt lgkmcnt(0)
	s_barrier
; #define LAS __attribute__((address_space(3)))
; __device__ void passA(const Params& p, LAS unsigned char* lds, int wg) {
;     ...
;         if (st + 1 < 17) {
;             bool ic2; int ci2; const bf16_t* Kb2; const bf16_t* Vb2; passA_chunk(p, st + 1, b, h, dir, vs, ic2, ci2, Kb2, Vb2);
; #pragma unroll
;             for (int rep = 0; rep < 2; ++rep) { const int it = tid + rep * 512;
;                 vr[rep] = *(const u32x4*)(Vb2 + (size_t)it * 8);
;                 const int sq = (it & 15) | (((it >> 6) & 1) << 4), ko = ((it >> 4) & 3) | ((it >> 7) << 2); const bf16_t* src = Kb2 + (size_t)((sq >> 2) * 8 + (ko >> 2)) * 512 + ((sq & 3) * 16 + (ko & 3)) * 8;
;                 kr[rep][0] = *(const u32x4*)src; kr[rep][1] = *(const u32x4*)(src + 32); kr[rep][2] = *(const u32x4*)(src + 64); kr[rep][3] = *(const u32x4*)(src + 96); } }
; #pragma unroll
;         for (int a = 0; a < 2; ++a) { nacc[a] *= decay;
; #pragma unroll
;             for (int v = 0; v < 4; ++v) acc[a][v] *= decay; }
; #pragma unroll
;         for (int ks = 0; ks < 4; ++ks) { bf16x8 kf[2], vf[4];
; #pragma unroll
;             for (int kt = 0; kt < 2; ++kt) kf[kt] = *(const LAS bf16x8*)(Kt + (wid * 32 + 8 * (fr >> 2) + 4 * kt + (fr & 3)) * 136 + ks * 32 + fq * 8);
; #pragma unroll
;             for (int vt = 0; vt < 4; ++vt) vf[vt] = *(const LAS bf16x8*)(Ve + (vt * 16 + fr) * 136 + ks * 32 + fq * 8);
;             bf16x8 ef = *(const LAS bf16x8*)(eB + st * 128 + ks * 32 + fq * 8);
;             if (fr != 0) ef = (bf16x8){0, 0, 0, 0, 0, 0, 0, 0};
; #pragma unroll
;             for (int kt = 0; kt < 2; ++kt) {
; #pragma unroll
;                 for (int vt = 0; vt < 4; ++vt) acc[kt][vt] = __builtin_amdgcn_mfma_f32_16x16x32_bf16(kf[kt], vf[vt], acc[kt][vt], 0, 0, 0);
;                 nacc[kt] = __builtin_amdgcn_mfma_f32_16x16x32_bf16(kf[kt], ef, nacc[kt], 0, 0, 0); } }
	ds_read_b128 v[44:47], v110
	ds_read_b128 v[48:51], v29
	v_pk_mul_f32 v[34:35], v[54:55], v[28:29] op_sel_hi:[1,0]
	v_pk_mul_f32 v[32:33], v[52:53], v[28:29] op_sel_hi:[1,0]
	ds_read_b128 v[52:55], v29 offset:4352
	ds_read_b128 v[58:61], v110 offset:64
	ds_read_b128 v[62:65], v29 offset:64
	ds_read_b128 v[66:69], v110 offset:1088
	ds_read_b128 v[70:73], v29 offset:8704
	ds_read_b128 v[74:77], v29 offset:4416
	ds_read_b128 v[92:95], v30 offset:256
	ds_read_b128 v[96:99], v29 offset:13056
	ds_read_b128 v[114:117], v29 offset:8768
	v_pk_mul_f32 v[38:39], v[136:137], v[28:29] op_sel_hi:[1,0]
	v_pk_mul_f32 v[36:37], v[134:135], v[28:29] op_sel_hi:[1,0]
	s_waitcnt lgkmcnt(2)
	v_cndmask_b32_e64 v95, 0, v95, s[0:1]
	v_cndmask_b32_e64 v94, 0, v94, s[0:1]
	v_cndmask_b32_e64 v93, 0, v93, s[0:1]
	v_cndmask_b32_e64 v92, 0, v92, s[0:1]
	v_mfma_f32_16x16x32_bf16 v[36:39], v[44:47], v[48:51], v[36:39]
	ds_read_b128 v[118:121], v30 offset:320
	ds_read_b128 v[122:125], v29 offset:13120
	v_pk_mul_f32 v[22:23], v[22:23], v[28:29] op_sel_hi:[1,0]
	v_mfma_f32_16x16x32_bf16 v[40:43], v[44:47], v[52:55], v[40:43]
	v_mul_f32_e64 v20, v20, v28
	v_mul_f32_e64 v21, v21, v28
	s_lshl_b64 s[14:15], s[14:15], 16
	s_add_u32 s14, s30, s14
	v_mfma_f32_16x16x32_bf16 v[16:19], v[44:47], v[70:73], v[16:19]
	s_addc_u32 s15, s31, s15
	s_ashr_i32 s13, s12, 31
	s_lshl_b64 s[12:13], s[12:13], 18
	s_waitcnt lgkmcnt(3)
	v_mfma_f32_16x16x32_bf16 v[24:27], v[44:47], v[96:99], v[24:27]
	s_add_u32 s11, s16, s12
	s_addc_u32 s13, s17, s13
	s_add_u32 s12, s11, s10
	v_mfma_f32_16x16x32_bf16 v[32:35], v[44:47], v[92:95], v[32:35]
	ds_read_b128 v[44:47], v110 offset:1152
	s_addc_u32 s13, s13, 0
	v_ashrrev_i32_e32 v91, 31, v90
	v_mfma_f32_16x16x32_bf16 v[4:7], v[66:69], v[52:55], v[4:7]
	ds_read_b128 v[52:55], v110 offset:128
	v_mfma_f32_16x16x32_bf16 v[0:3], v[66:69], v[48:51], v[0:3]
	s_waitcnt lgkmcnt(3)
	v_cndmask_b32_e64 v51, 0, v121, s[0:1]
	v_cndmask_b32_e64 v50, 0, v120, s[0:1]
	v_cndmask_b32_e64 v49, 0, v119, s[0:1]
	v_mfma_f32_16x16x32_bf16 v[8:11], v[66:69], v[70:73], v[8:11]
	v_cndmask_b32_e64 v48, 0, v118, s[0:1]
	v_mfma_f32_16x16x32_bf16 v[12:15], v[66:69], v[96:99], v[12:15]
	v_mfma_f32_16x16x32_bf16 v[20:23], v[66:69], v[92:95], v[20:23]
	v_mfma_f32_16x16x32_bf16 v[36:39], v[58:61], v[62:65], v[36:39]
	v_mfma_f32_16x16x32_bf16 v[40:43], v[58:61], v[74:77], v[40:43]
	v_mfma_f32_16x16x32_bf16 v[16:19], v[58:61], v[114:117], v[16:19]
	s_waitcnt lgkmcnt(2)
	v_mfma_f32_16x16x32_bf16 v[24:27], v[58:61], v[122:125], v[24:27]
	v_mfma_f32_16x16x32_bf16 v[32:35], v[58:61], v[48:51], v[32:35]
	ds_read_b128 v[58:61], v29 offset:128
	s_waitcnt lgkmcnt(2)
	v_mfma_f32_16x16x32_bf16 v[0:3], v[44:47], v[62:65], v[0:3]
	v_mfma_f32_16x16x32_bf16 v[4:7], v[44:47], v[74:77], v[4:7]
	v_mfma_f32_16x16x32_bf16 v[8:11], v[44:47], v[114:117], v[8:11]
	v_mfma_f32_16x16x32_bf16 v[12:15], v[44:47], v[122:125], v[12:15]
	v_mfma_f32_16x16x32_bf16 v[20:23], v[44:47], v[48:51], v[20:23]
	ds_read_b128 v[44:47], v29 offset:4480
	ds_read_b128 v[48:51], v110 offset:192
	ds_read_b128 v[92:95], v29 offset:192
	ds_read_b128 v[62:65], v110 offset:1216
	ds_read_b128 v[66:69], v29 offset:8832
	ds_read_b128 v[96:99], v29 offset:4544
	ds_read_b128 v[70:73], v30 offset:384
	ds_read_b128 v[74:77], v29 offset:13184
	ds_read_b128 v[114:117], v29 offset:8896
	ds_read_b128 v[118:121], v30 offset:448
	ds_read_b128 v[122:125], v29 offset:13248
	s_waitcnt lgkmcnt(11)
	v_mfma_f32_16x16x32_bf16 v[36:39], v[52:55], v[58:61], v[36:39]
	s_waitcnt lgkmcnt(4)
	v_cndmask_b32_e64 v31, 0, v73, s[0:1]
	v_cndmask_b32_e64 v30, 0, v72, s[0:1]
	v_cndmask_b32_e64 v29, 0, v71, s[0:1]
	v_cndmask_b32_e64 v28, 0, v70, s[0:1]
	v_mfma_f32_16x16x32_bf16 v[40:43], v[52:55], v[44:47], v[40:43]
	s_waitcnt lgkmcnt(1)
	v_cndmask_b32_e64 v121, 0, v121, s[0:1]
	v_cndmask_b32_e64 v120, 0, v120, s[0:1]
	v_cndmask_b32_e64 v119, 0, v119, s[0:1]
	v_mfma_f32_16x16x32_bf16 v[16:19], v[52:55], v[66:69], v[16:19]
	v_cndmask_b32_e64 v118, 0, v118, s[0:1]
	ds_read_b128 v[126:129], v110 offset:1280
	v_mfma_f32_16x16x32_bf16 v[24:27], v[52:55], v[74:77], v[24:27]
	v_mfma_f32_16x16x32_bf16 v[32:35], v[52:55], v[28:31], v[32:35]
	v_mfma_f32_16x16x32_bf16 v[138:141], v[62:65], v[28:31], v[20:23]
	v_lshl_add_u64 v[28:29], s[14:15], 0, v[82:83]
	s_mov_b64 s[14:15], 0x2000
	v_mfma_f32_16x16x32_bf16 v[52:55], v[62:65], v[58:61], v[0:3]
	v_lshl_add_u64 v[20:21], v[28:29], 0, v[86:87]
	v_lshl_add_u64 v[22:23], s[12:13], 0, v[84:85]
	v_mfma_f32_16x16x32_bf16 v[134:137], v[62:65], v[74:77], v[12:15]
	v_lshl_add_u64 v[0:1], s[12:13], 0, v[80:81]
	s_add_u32 s12, s70, 0xbc00000
	s_addc_u32 s13, s71, 0
	v_mfma_f32_16x16x32_bf16 v[72:75], v[48:51], v[92:95], v[36:39]
	s_cmp_lt_i32 s26, 32
	s_mov_b32 s26, 0xffff
	s_nop 0
	v_lshl_add_u64 v[36:37], v[28:29], 0, v[88:89]
	v_mfma_f32_16x16x32_bf16 v[58:61], v[62:65], v[44:47], v[4:7]
	v_mfma_f32_16x16x32_bf16 v[130:133], v[62:65], v[66:69], v[8:11]
	s_nop 2
	global_load_dwordx4 v[8:11], v[0:1], off
	s_nop 0
	global_load_dwordx4 v[0:3], v[20:21], off
	global_load_dwordx4 v[4:7], v[20:21], off offset:64
	global_load_dwordx4 v[12:15], v[20:21], off offset:128
	v_mfma_f32_16x16x32_bf16 v[68:71], v[48:51], v[96:99], v[40:43]
	v_mfma_f32_16x16x32_bf16 v[64:67], v[48:51], v[114:117], v[16:19]
	s_nop 2
	global_load_dwordx4 v[16:19], v[20:21], off offset:192
	s_nop 0
	global_load_dwordx4 v[20:23], v[22:23], off
	s_waitcnt lgkmcnt(1)
	v_mfma_f32_16x16x32_bf16 v[40:43], v[48:51], v[122:125], v[24:27]
	s_nop 2
	global_load_dwordx4 v[24:27], v[36:37], off
	global_load_dwordx4 v[28:31], v[36:37], off offset:64
	v_mfma_f32_16x16x32_bf16 v[76:79], v[48:51], v[118:121], v[32:35]
	s_nop 2
	global_load_dwordx4 v[32:35], v[36:37], off offset:128
	s_nop 0
	global_load_dwordx4 v[36:39], v[36:37], off offset:192
	s_waitcnt lgkmcnt(0)
	s_barrier
; #define LAS __attribute__((address_space(3)))
; __device__ __forceinline__ unsigned cvt_pk_bf16(float lo, float hi) { unsigned r; asm volatile("v_cvt_pk_bf16_f32 %0, %1, %2" : "=v"(r) : "v"(lo), "v"(hi)); return r; }
; __device__ void passA(const Params& p, LAS unsigned char* lds, int wg) {
;     ...
;         bool isctx; int ci; const bf16_t* Kb; const bf16_t* Vb; passA_chunk(p, st, b, h, dir, vs, isctx, ci, Kb, Vb);
;         if (!isctx) {
;             bf16_t* cs = cst_ptr(p, sid, ci);
; #pragma unroll
;             for (int vt = 0; vt < 4; ++vt) { u32x4 w; w.x = cvt_pk_bf16(acc[0][vt][0], acc[0][vt][1]); w.y = cvt_pk_bf16(acc[0][vt][2], acc[0][vt][3]);
;                 w.z = cvt_pk_bf16(acc[1][vt][0], acc[1][vt][1]); w.w = cvt_pk_bf16(acc[1][vt][2], acc[1][vt][3]);
;                 __builtin_nontemporal_store(w, (u32x4*)(cs + (size_t)((vs * 4 + vt) * 8 + wid) * 512 + (fr * 4 + fq) * 8)); }
;             if (vs == 0) { if (fr == 0) { float* np = (float*)(p.ws + OFF_NST) + (size_t)(sid * 16 + ci) * 256 + wid * 32 + fq * 8; *(f32x4*)np = nacc[0]; *(f32x4*)(np + 4) = nacc[1]; }
;                 if (tid == 0) ((float*)(p.ws + OFF_MST))[sid * 16 + ci] = mprevA[st]; }
;     ...
;         for (int ks = 0; ks < 4; ++ks) { bf16x8 kf[2], vf[4];
; #pragma unroll
;             for (int kt = 0; kt < 2; ++kt) kf[kt] = *(const LAS bf16x8*)(Kt + (wid * 32 + 8 * (fr >> 2) + 4 * kt + (fr & 3)) * 136 + ks * 32 + fq * 8);
; #pragma unroll
;             for (int vt = 0; vt < 4; ++vt) vf[vt] = *(const LAS bf16x8*)(Ve + (vt * 16 + fr) * 136 + ks * 32 + fq * 8);
;             bf16x8 ef = *(const LAS bf16x8*)(eB + st * 128 + ks * 32 + fq * 8);
;             if (fr != 0) ef = (bf16x8){0, 0, 0, 0, 0, 0, 0, 0};
; #pragma unroll
;             for (int kt = 0; kt < 2; ++kt) {
; #pragma unroll
;                 for (int vt = 0; vt < 4; ++vt) acc[kt][vt] = __builtin_amdgcn_mfma_f32_16x16x32_bf16(kf[kt], vf[vt], acc[kt][vt], 0, 0, 0);
;                 nacc[kt] = __builtin_amdgcn_mfma_f32_16x16x32_bf16(kf[kt], ef, nacc[kt], 0, 0, 0); } }
	v_mfma_f32_16x16x32_bf16 v[44:47], v[126:129], v[92:95], v[52:55]
	v_lshl_add_u32 v92, s34, 5, v56
	v_ashrrev_i32_e32 v93, 31, v92
	v_lshlrev_b64 v[92:93], 10, v[92:93]
	v_lshl_add_u64 v[94:95], v[92:93], 0, s[14:15]
	s_mov_b64 s[14:15], 0x4000
	v_mfma_f32_16x16x32_bf16 v[48:51], v[126:129], v[96:99], v[58:61]
	v_lshl_add_u64 v[96:97], v[92:93], 0, s[14:15]
	s_mov_b64 s[14:15], 0x6000
	v_lshl_add_u64 v[98:99], v[92:93], 0, s[14:15]
	s_cselect_b32 s15, s69, s13
	s_cselect_b32 s14, s68, s12
	s_add_u32 s41, s16, s10
	s_addc_u32 s46, s17, 0
	v_mfma_f32_16x16x32_bf16 v[52:55], v[126:129], v[114:117], v[130:133]
	v_and_b32_e32 v114, 24, v57
	s_add_u32 s16, s70, 0xfd20000
	v_lshlrev_b32_e32 v101, 1, v114
	v_mfma_f32_16x16x32_bf16 v[56:59], v[126:129], v[122:125], v[134:137]
	s_addc_u32 s17, s71, 0
	v_mul_u32_u24_e32 v115, 0x110, v100
	v_lshl_or_b32 v100, v100, 6, v101
	v_mfma_f32_16x16x32_bf16 v[60:63], v[126:129], v[118:121], v[138:141]
	v_mov_b32_e32 v101, v83
	v_lshl_add_u64 v[90:91], v[90:91], 2, s[16:17]
	v_lshlrev_b32_e32 v82, 2, v114
	v_lshl_add_u64 v[100:101], s[14:15], 0, v[100:101]
	v_lshl_add_u64 v[90:91], v[90:91], 0, v[82:83]
	s_add_u32 s14, s70, 0xfe20000
	v_lshlrev_b32_e32 v82, 5, v112
	s_movk_i32 s10, 0x180
	s_addc_u32 s15, s71, 0
	v_and_or_b32 v112, v111, s10, v82
	v_add_u32_e32 v111, v113, v115
	s_mov_b32 s54, 0x05040100
	s_mov_b32 s55, 0x07060302
	s_nop 0
	s_branch .LBB0_392
